# v76 plus gla_g3 load hoists (q/k/v/state and epilogue gate loads) and nt hint on all Resid-epilogue residual stores
# speedup vs baseline: 1.0003x; 1.0003x over previous
.LBB0_484:
	s_or_b64 exec, exec, s[28:29]
	s_waitcnt lgkmcnt(0)
	v_lshl_add_u64 v[66:67], v[156:157], 0, s[68:69]
	v_readlane_b32 s28, v253, 40
	v_lshlrev_b64 v[68:69], 11, v[66:67]
	v_readlane_b32 s29, v253, 41
	s_nop 1
	v_lshl_add_u64 v[68:69], s[28:29], 0, v[68:69]
	v_lshl_add_u64 v[68:69], s[2:3], 1, v[68:69]
	v_lshl_add_u64 v[68:69], v[68:69], 0, s[94:95]
	v_lshl_add_u64 v[72:73], v[68:69], 0, v[0:1]
	global_load_dwordx4 v[68:71], v[72:73], off
	s_waitcnt vmcnt(0)
	v_lshlrev_b32_e32 v74, 16, v68
	v_and_b32_e32 v75, 0xffff0000, v68
	v_lshlrev_b32_e32 v68, 16, v69
	v_and_b32_e32 v69, 0xffff0000, v69
	v_pk_add_f32 v[68:69], v[64:65], v[68:69]
	v_lshlrev_b32_e32 v64, 16, v70
	v_and_b32_e32 v65, 0xffff0000, v70
	v_pk_add_f32 v[62:63], v[62:63], v[74:75]
	v_pk_add_f32 v[74:75], v[58:59], v[64:65]
	v_lshlrev_b32_e32 v58, 16, v71
	v_and_b32_e32 v59, 0xffff0000, v71
	v_pk_add_f32 v[70:71], v[60:61], v[58:59]
	v_cvt_pk_bf16_f32 v58, v62, v63
	v_cvt_pk_bf16_f32 v59, v68, v69
	v_cvt_pk_bf16_f32 v60, v74, v75
	v_cvt_pk_bf16_f32 v61, v70, v71
	global_store_dwordx4 v[72:73], v[58:61], off nt
	v_pk_mul_f32 v[64:65], v[62:63], v[62:63]
	v_pk_mul_f32 v[62:63], v[68:69], v[68:69]
	v_pk_mul_f32 v[58:59], v[70:71], v[70:71]
	global_load_dwordx4 v[68:71], v[72:73], off offset:256
	v_pk_mul_f32 v[60:61], v[74:75], v[74:75]
	s_waitcnt vmcnt(0)
	v_lshlrev_b32_e32 v74, 16, v68
	v_and_b32_e32 v75, 0xffff0000, v68
	v_lshlrev_b32_e32 v68, 16, v69
	v_and_b32_e32 v69, 0xffff0000, v69
	v_pk_add_f32 v[56:57], v[56:57], v[68:69]
	v_lshlrev_b32_e32 v68, 16, v70
	v_and_b32_e32 v69, 0xffff0000, v70
	v_pk_add_f32 v[68:69], v[50:51], v[68:69]
	v_lshlrev_b32_e32 v50, 16, v71
	v_and_b32_e32 v51, 0xffff0000, v71
	v_pk_add_f32 v[54:55], v[54:55], v[74:75]
	v_pk_add_f32 v[70:71], v[52:53], v[50:51]
	v_cvt_pk_bf16_f32 v50, v54, v55
	v_cvt_pk_bf16_f32 v51, v56, v57
	v_cvt_pk_bf16_f32 v52, v68, v69
	v_cvt_pk_bf16_f32 v53, v70, v71
	global_store_dwordx4 v[72:73], v[50:53], off offset:256 nt
	s_nop 1
	v_pk_mul_f32 v[50:51], v[54:55], v[54:55]
	v_pk_mul_f32 v[52:53], v[56:57], v[56:57]
	v_add_f32_e32 v50, v50, v51
	v_add_f32_e32 v51, v64, v65
	v_add_f32_e32 v50, v52, v50
	v_add_f32_e32 v51, v62, v51
	v_pk_mul_f32 v[54:55], v[68:69], v[68:69]
	v_add_f32_e32 v50, v53, v50
	v_add_f32_e32 v51, v63, v51
	v_add_f32_e32 v50, v54, v50
	v_add_f32_e32 v51, v60, v51
	v_pk_mul_f32 v[56:57], v[70:71], v[70:71]
	v_add_f32_e32 v50, v55, v50
	v_add_f32_e32 v51, v61, v51
	v_add_f32_e32 v50, v56, v50
	v_add_f32_e32 v51, v58, v51
	v_add_f32_e32 v50, v57, v50
	v_add_f32_e32 v51, v59, v51
	v_add_f32_e32 v50, v51, v50
	ds_bpermute_b32 v51, v161, v50
	s_waitcnt lgkmcnt(0)
	v_add_f32_e32 v50, v50, v51
	ds_bpermute_b32 v51, v160, v50
	s_and_saveexec_b64 s[28:29], s[38:39]
	s_cbranch_execz .LBB0_486
	v_readlane_b32 s58, v252, 43
	v_lshlrev_b64 v[52:53], 6, v[66:67]
	v_readlane_b32 s59, v252, 44
	s_waitcnt lgkmcnt(0)
	v_add_f32_e32 v50, v50, v51
	v_lshl_add_u64 v[52:53], s[58:59], 0, v[52:53]
	v_lshl_add_u64 v[52:53], s[52:53], 2, v[52:53]
	s_lshl_b32 s58, s91, 2
	s_mov_b32 s59, s95
	v_lshl_add_u64 v[52:53], v[52:53], 0, s[58:59]
	global_store_dword v[52:53], v50, off nt
.LBB0_486:
	s_or_b64 exec, exec, s[28:29]
	s_mov_b64 s[28:29], 0x90
	s_waitcnt lgkmcnt(0)
	v_lshl_add_u64 v[50:51], v[156:157], 0, s[28:29]
	v_readlane_b32 s28, v253, 40
	v_lshlrev_b64 v[52:53], 11, v[50:51]
	v_readlane_b32 s29, v253, 41
	s_nop 1
	v_lshl_add_u64 v[52:53], s[28:29], 0, v[52:53]
	v_lshl_add_u64 v[52:53], s[2:3], 1, v[52:53]
	v_lshl_add_u64 v[52:53], v[52:53], 0, s[94:95]
	v_lshl_add_u64 v[56:57], v[52:53], 0, v[0:1]
	global_load_dwordx4 v[52:55], v[56:57], off
	s_waitcnt vmcnt(0)
	v_lshlrev_b32_e32 v58, 16, v52
	v_and_b32_e32 v59, 0xffff0000, v52
	v_lshlrev_b32_e32 v52, 16, v53
	v_and_b32_e32 v53, 0xffff0000, v53
	v_pk_add_f32 v[52:53], v[48:49], v[52:53]
	v_lshlrev_b32_e32 v48, 16, v54
	v_and_b32_e32 v49, 0xffff0000, v54
	v_pk_add_f32 v[46:47], v[46:47], v[58:59]
	v_pk_add_f32 v[58:59], v[42:43], v[48:49]
	v_lshlrev_b32_e32 v42, 16, v55
	v_and_b32_e32 v43, 0xffff0000, v55
	v_pk_add_f32 v[54:55], v[44:45], v[42:43]
	v_cvt_pk_bf16_f32 v42, v46, v47
	v_cvt_pk_bf16_f32 v43, v52, v53
	v_cvt_pk_bf16_f32 v44, v58, v59
	v_cvt_pk_bf16_f32 v45, v54, v55
	global_store_dwordx4 v[56:57], v[42:45], off nt
	v_pk_mul_f32 v[48:49], v[46:47], v[46:47]
	v_pk_mul_f32 v[46:47], v[52:53], v[52:53]
	v_pk_mul_f32 v[42:43], v[54:55], v[54:55]
	global_load_dwordx4 v[52:55], v[56:57], off offset:256
	v_pk_mul_f32 v[44:45], v[58:59], v[58:59]
	s_waitcnt vmcnt(0)
	v_lshlrev_b32_e32 v58, 16, v52
	v_and_b32_e32 v59, 0xffff0000, v52
	v_lshlrev_b32_e32 v52, 16, v53
	v_and_b32_e32 v53, 0xffff0000, v53
	v_pk_add_f32 v[40:41], v[40:41], v[52:53]
	v_lshlrev_b32_e32 v52, 16, v54
	v_and_b32_e32 v53, 0xffff0000, v54
	v_pk_add_f32 v[52:53], v[34:35], v[52:53]
	v_lshlrev_b32_e32 v34, 16, v55
	v_and_b32_e32 v35, 0xffff0000, v55
	v_pk_add_f32 v[38:39], v[38:39], v[58:59]
	v_pk_add_f32 v[54:55], v[36:37], v[34:35]
	v_cvt_pk_bf16_f32 v34, v38, v39
	v_cvt_pk_bf16_f32 v35, v40, v41
	v_cvt_pk_bf16_f32 v36, v52, v53
	v_cvt_pk_bf16_f32 v37, v54, v55
	global_store_dwordx4 v[56:57], v[34:37], off offset:256 nt
	s_nop 1
	v_pk_mul_f32 v[34:35], v[38:39], v[38:39]
	v_pk_mul_f32 v[36:37], v[40:41], v[40:41]
	v_add_f32_e32 v34, v34, v35
	v_add_f32_e32 v35, v48, v49
	v_add_f32_e32 v34, v36, v34
	v_add_f32_e32 v35, v46, v35
	v_pk_mul_f32 v[38:39], v[52:53], v[52:53]
	v_add_f32_e32 v34, v37, v34
	v_add_f32_e32 v35, v47, v35
	v_add_f32_e32 v34, v38, v34
	v_add_f32_e32 v35, v44, v35
	v_pk_mul_f32 v[40:41], v[54:55], v[54:55]
	v_add_f32_e32 v34, v39, v34
	v_add_f32_e32 v35, v45, v35
	v_add_f32_e32 v34, v40, v34
	v_add_f32_e32 v35, v42, v35
	v_add_f32_e32 v34, v41, v34
	v_add_f32_e32 v35, v43, v35
	v_add_f32_e32 v34, v35, v34
	ds_bpermute_b32 v35, v161, v34
	s_waitcnt lgkmcnt(0)
	v_add_f32_e32 v34, v34, v35
	ds_bpermute_b32 v35, v160, v34
	s_and_saveexec_b64 s[28:29], s[38:39]
	s_cbranch_execz .LBB0_488
	v_readlane_b32 s58, v252, 43
	v_lshlrev_b64 v[36:37], 6, v[50:51]
	v_readlane_b32 s59, v252, 44
	s_waitcnt lgkmcnt(0)
	v_add_f32_e32 v34, v34, v35
	v_lshl_add_u64 v[36:37], s[58:59], 0, v[36:37]
	v_lshl_add_u64 v[36:37], s[52:53], 2, v[36:37]
	s_lshl_b32 s58, s91, 2
	s_mov_b32 s59, s95
	v_lshl_add_u64 v[36:37], v[36:37], 0, s[58:59]
	global_store_dword v[36:37], v34, off nt
.LBB0_488:
	s_or_b64 exec, exec, s[28:29]
	s_mov_b64 s[28:29], 0xa0
	s_waitcnt lgkmcnt(0)
	v_lshl_add_u64 v[34:35], v[156:157], 0, s[28:29]
	v_readlane_b32 s28, v253, 40
	v_lshlrev_b64 v[36:37], 11, v[34:35]
	v_readlane_b32 s29, v253, 41
	s_nop 1
	v_lshl_add_u64 v[36:37], s[28:29], 0, v[36:37]
	v_lshl_add_u64 v[36:37], s[2:3], 1, v[36:37]
	v_lshl_add_u64 v[36:37], v[36:37], 0, s[94:95]
	v_lshl_add_u64 v[40:41], v[36:37], 0, v[0:1]
	global_load_dwordx4 v[36:39], v[40:41], off
	s_waitcnt vmcnt(0)
	v_lshlrev_b32_e32 v42, 16, v36
	v_and_b32_e32 v43, 0xffff0000, v36
	v_lshlrev_b32_e32 v36, 16, v37
	v_and_b32_e32 v37, 0xffff0000, v37
	v_pk_add_f32 v[36:37], v[32:33], v[36:37]
	v_lshlrev_b32_e32 v32, 16, v38
	v_and_b32_e32 v33, 0xffff0000, v38
	v_pk_add_f32 v[30:31], v[30:31], v[42:43]
	v_pk_add_f32 v[42:43], v[26:27], v[32:33]
	v_lshlrev_b32_e32 v26, 16, v39
	v_and_b32_e32 v27, 0xffff0000, v39
	v_pk_add_f32 v[38:39], v[28:29], v[26:27]
	v_cvt_pk_bf16_f32 v26, v30, v31
	v_cvt_pk_bf16_f32 v27, v36, v37
	v_cvt_pk_bf16_f32 v28, v42, v43
	v_cvt_pk_bf16_f32 v29, v38, v39
	global_store_dwordx4 v[40:41], v[26:29], off nt
	v_pk_mul_f32 v[32:33], v[30:31], v[30:31]
	v_pk_mul_f32 v[30:31], v[36:37], v[36:37]
	v_pk_mul_f32 v[26:27], v[38:39], v[38:39]
	global_load_dwordx4 v[36:39], v[40:41], off offset:256
	v_pk_mul_f32 v[28:29], v[42:43], v[42:43]
	s_waitcnt vmcnt(0)
	v_lshlrev_b32_e32 v42, 16, v36
	v_and_b32_e32 v43, 0xffff0000, v36
	v_lshlrev_b32_e32 v36, 16, v37
	v_and_b32_e32 v37, 0xffff0000, v37
	v_pk_add_f32 v[24:25], v[24:25], v[36:37]
	v_lshlrev_b32_e32 v36, 16, v38
	v_and_b32_e32 v37, 0xffff0000, v38
	v_pk_add_f32 v[36:37], v[18:19], v[36:37]
	v_lshlrev_b32_e32 v18, 16, v39
	v_and_b32_e32 v19, 0xffff0000, v39
	v_pk_add_f32 v[22:23], v[22:23], v[42:43]
	v_pk_add_f32 v[38:39], v[20:21], v[18:19]
	v_cvt_pk_bf16_f32 v18, v22, v23
	v_cvt_pk_bf16_f32 v19, v24, v25
	v_cvt_pk_bf16_f32 v20, v36, v37
	v_cvt_pk_bf16_f32 v21, v38, v39
	global_store_dwordx4 v[40:41], v[18:21], off offset:256 nt
	s_nop 1
	v_pk_mul_f32 v[18:19], v[22:23], v[22:23]
	v_pk_mul_f32 v[20:21], v[24:25], v[24:25]
	v_add_f32_e32 v18, v18, v19
	v_add_f32_e32 v19, v32, v33
	v_add_f32_e32 v18, v20, v18
	v_add_f32_e32 v19, v30, v19
	v_pk_mul_f32 v[22:23], v[36:37], v[36:37]
	v_add_f32_e32 v18, v21, v18
	v_add_f32_e32 v19, v31, v19
	v_add_f32_e32 v18, v22, v18
	v_add_f32_e32 v19, v28, v19
	v_pk_mul_f32 v[24:25], v[38:39], v[38:39]
	v_add_f32_e32 v18, v23, v18
	v_add_f32_e32 v19, v29, v19
	v_add_f32_e32 v18, v24, v18
	v_add_f32_e32 v19, v26, v19
	v_add_f32_e32 v18, v25, v18
	v_add_f32_e32 v19, v27, v19
	v_add_f32_e32 v18, v19, v18
	ds_bpermute_b32 v19, v161, v18
	s_waitcnt lgkmcnt(0)
	v_add_f32_e32 v18, v18, v19
	ds_bpermute_b32 v19, v160, v18
	s_and_saveexec_b64 s[28:29], s[38:39]
	s_cbranch_execz .LBB0_490
	v_readlane_b32 s58, v252, 43
	v_lshlrev_b64 v[20:21], 6, v[34:35]
	v_readlane_b32 s59, v252, 44
	s_waitcnt lgkmcnt(0)
	v_add_f32_e32 v18, v18, v19
	v_lshl_add_u64 v[20:21], s[58:59], 0, v[20:21]
	v_lshl_add_u64 v[20:21], s[52:53], 2, v[20:21]
	s_lshl_b32 s58, s91, 2
	s_mov_b32 s59, s95
	v_lshl_add_u64 v[20:21], v[20:21], 0, s[58:59]
	global_store_dword v[20:21], v18, off nt
.LBB0_490:
	s_or_b64 exec, exec, s[28:29]
	s_mov_b64 s[28:29], 0xb0
	s_waitcnt lgkmcnt(0)
	v_lshl_add_u64 v[18:19], v[156:157], 0, s[28:29]
	v_readlane_b32 s28, v253, 40
	v_lshlrev_b64 v[20:21], 11, v[18:19]
	v_readlane_b32 s29, v253, 41
	s_nop 1
	v_lshl_add_u64 v[20:21], s[28:29], 0, v[20:21]
	v_lshl_add_u64 v[20:21], s[2:3], 1, v[20:21]
	v_lshl_add_u64 v[20:21], v[20:21], 0, s[94:95]
	v_lshl_add_u64 v[24:25], v[20:21], 0, v[0:1]
	global_load_dwordx4 v[20:23], v[24:25], off
	s_waitcnt vmcnt(0)
	v_lshlrev_b32_e32 v26, 16, v20
	v_and_b32_e32 v27, 0xffff0000, v20
	v_lshlrev_b32_e32 v20, 16, v21
	v_and_b32_e32 v21, 0xffff0000, v21
	v_pk_add_f32 v[20:21], v[16:17], v[20:21]
	v_lshlrev_b32_e32 v16, 16, v22
	v_and_b32_e32 v17, 0xffff0000, v22
	v_pk_add_f32 v[14:15], v[14:15], v[26:27]
	v_pk_add_f32 v[26:27], v[10:11], v[16:17]
	v_lshlrev_b32_e32 v10, 16, v23
	v_and_b32_e32 v11, 0xffff0000, v23
	v_pk_add_f32 v[22:23], v[12:13], v[10:11]
	v_cvt_pk_bf16_f32 v10, v14, v15
	v_cvt_pk_bf16_f32 v11, v20, v21
	v_cvt_pk_bf16_f32 v12, v26, v27
	v_cvt_pk_bf16_f32 v13, v22, v23
	global_store_dwordx4 v[24:25], v[10:13], off nt
	v_pk_mul_f32 v[16:17], v[14:15], v[14:15]
	v_pk_mul_f32 v[14:15], v[20:21], v[20:21]
	v_pk_mul_f32 v[10:11], v[22:23], v[22:23]
	global_load_dwordx4 v[20:23], v[24:25], off offset:256
	v_pk_mul_f32 v[12:13], v[26:27], v[26:27]
	s_waitcnt vmcnt(0)
	v_lshlrev_b32_e32 v26, 16, v20
	v_and_b32_e32 v27, 0xffff0000, v20
	v_lshlrev_b32_e32 v20, 16, v21
	v_and_b32_e32 v21, 0xffff0000, v21
	v_pk_add_f32 v[8:9], v[8:9], v[20:21]
	v_lshlrev_b32_e32 v20, 16, v22
	v_and_b32_e32 v21, 0xffff0000, v22
	v_pk_add_f32 v[20:21], v[2:3], v[20:21]
	v_lshlrev_b32_e32 v2, 16, v23
	v_and_b32_e32 v3, 0xffff0000, v23
	v_pk_add_f32 v[6:7], v[6:7], v[26:27]
	v_pk_add_f32 v[22:23], v[4:5], v[2:3]
	v_cvt_pk_bf16_f32 v2, v6, v7
	v_cvt_pk_bf16_f32 v3, v8, v9
	v_cvt_pk_bf16_f32 v4, v20, v21
	v_cvt_pk_bf16_f32 v5, v22, v23
	global_store_dwordx4 v[24:25], v[2:5], off offset:256 nt
	s_nop 1
	v_pk_mul_f32 v[2:3], v[6:7], v[6:7]
	v_pk_mul_f32 v[4:5], v[8:9], v[8:9]
	v_add_f32_e32 v0, v2, v3
	v_add_f32_e32 v2, v16, v17
	v_add_f32_e32 v0, v4, v0
	v_add_f32_e32 v2, v14, v2
	v_pk_mul_f32 v[6:7], v[20:21], v[20:21]
	v_add_f32_e32 v0, v5, v0
	v_add_f32_e32 v2, v15, v2
	v_add_f32_e32 v0, v6, v0
	v_add_f32_e32 v2, v12, v2
	v_pk_mul_f32 v[8:9], v[22:23], v[22:23]
	v_add_f32_e32 v0, v7, v0
	v_add_f32_e32 v2, v13, v2
	v_add_f32_e32 v0, v8, v0
	v_add_f32_e32 v2, v10, v2
	v_add_f32_e32 v0, v9, v0
	v_add_f32_e32 v2, v11, v2
	v_add_f32_e32 v0, v2, v0
	ds_bpermute_b32 v2, v161, v0
	s_waitcnt lgkmcnt(0)
	v_add_f32_e32 v0, v0, v2
	ds_bpermute_b32 v2, v160, v0
	s_and_saveexec_b64 s[2:3], s[38:39]
	s_cbranch_execz .LBB0_492
	v_readlane_b32 s28, v252, 43
	v_lshlrev_b64 v[4:5], 6, v[18:19]
	v_readlane_b32 s29, v252, 44
	s_lshl_b32 s94, s91, 2
	s_waitcnt lgkmcnt(0)
	v_add_f32_e32 v0, v0, v2
	v_lshl_add_u64 v[4:5], s[28:29], 0, v[4:5]
	v_lshl_add_u64 v[4:5], s[52:53], 2, v[4:5]
	v_lshl_add_u64 v[4:5], v[4:5], 0, s[94:95]
	global_store_dword v[4:5], v0, off nt
